# v32 with the P2/P3 first/last split keyed on permuted-id bit 2 (whole heads alternate) instead of bit 0
# speedup vs baseline: 1.0096x; 1.0096x over previous
; #define LAS __attribute__((address_space(3)))
; DI float bf2f(unsigned short u) { return __uint_as_float(((unsigned)u) << 16); }
; DI float gamma_of(int h) { return 1.0f - exp2f(-5.0f - (float)h); }
; DI void ret_decode_unit(LAS unsigned char* lds, const bf16_t* Z, const float* S0, float* S1, bf16_t* MIX, const float* rng, int b, int h, int tid) {
;     LAS float* qv = (LAS float*)lds; LAS float* red = qv + 768;
;     const int lane = tid & 63, wid = tid >> 6;
;     const bf16_t* zrow = Z + (size_t)(LP + b) * INW;
;     if (tid < 256) { qv[tid] = bf2f(zrow[C_RQ + h * 256 + tid]); qv[256 + tid] = bf2f(zrow[C_RK + h * 256 + tid]); qv[512 + tid] = bf2f(zrow[C_RV + h * 256 + tid]); }
;     __syncthreads();
;     const float gm = gamma_of(h);
;     const f32x4 v4 = *(const LAS f32x4*)(qv + 512 + 4 * lane);
;     f32x4 acc = {0.f, 0.f, 0.f, 0.f};
;     const size_t off = ((size_t)(b * 4 + h) * 256 + wid * 32) * 256 + 4 * lane;
;     const float* s0 = S0 + off; float* s1 = S1 + off;
; __global__ void __launch_bounds__(512, 2) fwd_kernel(Args a) {
;     ...
;     if (IN(2)) for (int rep_ = 0; rep_ < 1 + ((DUPMASK >> 2) & 1); ++rep_) { if (rep_) xcd_barrier(bar);
;         if (bx & 1) for (int u = bx; u < 256; u += G) ret_decode_unit(lds, Z, state0, out + O_SS, MIX, rng, u >> 2, u & 3, tid);
;         for (int u = bx; u < 256; u += G) ret_step1(lds, Z, KV, u >> 2, u & 3, tid);
;         if (!(bx & 1)) for (int u = bx; u < 256; u += G) ret_decode_unit(lds, Z, state0, out + O_SS, MIX, rng, u >> 2, u & 3, tid);
;     }
.LBB0_226:
	s_and_b32 s98, s92, 7
	s_lshl_b32 s98, s98, 5
	s_lshr_b32 s99, s92, 3
	s_or_b32 s92, s98, s99
	s_cmp_lt_i32 s62, 3
	s_cselect_b64 s[2:3], -1, 0
	s_add_u32 s56, s60, 0x8000000
	s_addc_u32 s57, s61, 0
	s_add_u32 s4, s60, 0xfc00000
	s_addc_u32 s5, s61, 0
	v_writelane_b32 v254, s4, 23
	s_and_b64 s[10:11], s[2:3], s[0:1]
	s_andn2_b64 vcc, exec, s[10:11]
	v_writelane_b32 v254, s5, 24
	v_lshrrev_b32_e32 v252, 6, v253
	v_cmp_gt_u32_e64 s[0:1], 64, v253
	s_cbranch_vccnz .LBB0_250
	s_bitcmp0_b32 s92, 2
	v_readlane_b32 s68, v254, 7
	s_cselect_b64 s[14:15], -1, 0
	s_cmpk_gt_i32 s92, 0xff
	v_readlane_b32 s82, v254, 21
	v_lshlrev_b32_e32 v0, 2, v253
	s_cselect_b64 s[2:3], -1, 0
	v_readlane_b32 s83, v254, 22
	s_add_u32 s12, s82, 0x5220000
	v_and_b32_e32 v147, 0xfc, v0
	v_readlane_b32 s72, v254, 11
	v_readlane_b32 s73, v254, 12
	s_addc_u32 s13, s83, 0
	s_movk_i32 s4, 0x100
	v_add_u32_e32 v146, 0, v0
	v_lshlrev_b32_e32 v20, 2, v147
	v_mov_b32_e32 v21, 0
	v_lshl_add_u32 v149, v252, 7, 0
	v_mul_u32_u24_e32 v0, 0x380, v252
	s_or_b64 s[2:3], s[14:15], s[2:3]
	s_mov_b32 s17, 0
	v_add_u32_e32 v144, 0x900, v253
	v_add_u32_e32 v145, 0xd00, v253
	v_cmp_gt_u32_e64 s[6:7], s4, v253
	v_add_u32_e32 v148, 0, v20
	v_lshl_or_b32 v128, v252, 13, v147
	v_mov_b32_e32 v129, v21
	v_add3_u32 v150, v149, v0, v20
	v_lshl_add_u64 v[130:131], s[72:73], 0, v[20:21]
	s_and_b64 vcc, exec, s[2:3]
	v_readlane_b32 s69, v254, 8
	v_readlane_b32 s70, v254, 9
	v_readlane_b32 s71, v254, 10
	v_readlane_b32 s74, v254, 13
	v_readlane_b32 s75, v254, 14
	v_readlane_b32 s76, v254, 15
	v_readlane_b32 s77, v254, 16
	v_readlane_b32 s78, v254, 17
	v_readlane_b32 s79, v254, 18
	v_readlane_b32 s80, v254, 19
	v_readlane_b32 s81, v254, 20
	s_cbranch_vccnz .LBB0_236
	v_mbcnt_lo_u32_b32 v0, -1, 0
	v_mov_b32_e32 v30, 0x42800000
	v_mov_b32_e32 v31, 0x358637bd
	v_mbcnt_hi_u32_b32 v32, -1, v0
	s_mov_b32 s18, s92
	s_branch .LBB0_230

; #define LAS __attribute__((address_space(3)))
; DI float bf2f(unsigned short u) { return __uint_as_float(((unsigned)u) << 16); }
; DI void attn_decode_unit(LAS unsigned char* lds, const bf16_t* Z, const float* ck, const float* cv, bf16_t* MIX, const float* gq, const float* gk, const float* sinks, float* o_k, float* o_v, int b, int kh, int tid) {
;     LAS float* Kc = (LAS float*)lds; LAS float* Vc = Kc + 129 * 68; LAS float* qs = Vc + 129 * 64; LAS float* pw = qs + 512;
;     const int lane = tid & 63, wid = tid >> 6;
; #pragma unroll
;     for (int k = 0; k < 4; ++k) {
;         const int it = k * 512 + tid, w = it >> 4, c4 = (it & 15) * 4;
;         const size_t src = ((size_t)(b * 128 + w) * 2 + kh) * 64 + c4;
;         const f32x4 k4 = *(const f32x4*)(ck + src), v4 = *(const f32x4*)(cv + src);
;         *(LAS f32x4*)(Kc + w * 68 + c4) = k4; *(LAS f32x4*)(Vc + w * 64 + c4) = v4;
;         if (w >= 1) { const size_t dst = ((size_t)(b * 128 + w - 1) * 2 + kh) * 64 + c4; *(f32x4*)(o_k + dst) = k4; *(f32x4*)(o_v + dst) = v4; }
;     }
;     const bf16_t* zrow = Z + (size_t)(LP + b) * INW;
;     const size_t dnew = ((size_t)(b * 128 + 127) * 2 + kh) * 64 + lane;
;     if (wid == 0) { const float kx = bf2f(zrow[C_AK + kh * 64 + lane]); const float ss = wave_sum(kx * kx); const float kn = kx * rsqrtf(ss * (1.0f / 64.0f) + EPS) * gk[lane];
;         Kc[128 * 68 + lane] = kn; o_k[dnew] = kn; }
;     if (wid == 1) { const float vx = bf2f(zrow[C_AV + kh * 64 + lane]); Vc[128 * 64 + lane] = vx; o_v[dnew] = vx; }
;     const int hq = kh * 8 + wid;
;     { const float qx = bf2f(zrow[hq * 64 + lane]); const float ss = wave_sum(qx * qx); qs[wid * 64 + lane] = qx * rsqrtf(ss * (1.0f / 64.0f) + EPS) * gq[lane] * 0.125f; }
; __global__ void __launch_bounds__(512, 2) fwd_kernel(Args a) {
;     ...
;         if (bx & 1) for (int u = bx; u < 256; u += G) attn_decode_unit(lds, Z, cache_k, cache_v, MIX, gq, gk, sinks, out + O_KS, out + O_VS, u >> 1, u & 1, tid);
;         for (int u = 256 + bx; u < 512; u += G) ret_decode_unit(lds, Z, state0, out + O_SS, MIX, rng, u >> 2, u & 3, tid);
;         if (!(bx & 1)) for (int u = bx; u < 256; u += G) attn_decode_unit(lds, Z, cache_k, cache_v, MIX, gq, gk, sinks, out + O_KS, out + O_VS, u >> 1, u & 1, tid);
.LBB0_310:
	v_readlane_b32 s0, v254, 39
	v_readlane_b32 s1, v254, 40
	s_or_b64 exec, exec, s[0:1]
	v_readlane_b32 s92, v254, 37
	s_bitcmp0_b32 s92, 2
	v_readlane_b32 s68, v254, 7
	s_cselect_b64 s[18:19], -1, 0
	s_cmpk_gt_i32 s92, 0xff
	v_readlane_b32 s82, v254, 21
	s_cselect_b64 s[4:5], -1, 0
	v_readlane_b32 s83, v254, 22
	s_add_u32 s14, s82, 0x4220000
	s_addc_u32 s15, s83, 0
	s_add_u32 s16, s82, 0x4a20000
	v_add_u32_e32 v3, 0x200, v253
	s_addc_u32 s17, s83, 0
	v_lshlrev_b32_e32 v0, 2, v253
	v_lshrrev_b32_e32 v42, 4, v3
	v_add_u32_e32 v3, 0x600, v253
	v_lshlrev_b32_e32 v8, 2, v152
	s_add_i32 s6, 0, 0x10a10
	v_lshrrev_b32_e32 v44, 4, v3
	v_add_u32_e32 v3, 0, v8
	v_add_u32_e32 v47, s6, v0
	s_movk_i32 s6, 0x10c
	s_add_i32 s7, 0, 0x11210
	v_and_b32_e32 v40, 60, v0
	v_lshrrev_b32_e32 v41, 4, v253
	v_mad_u32_u24 v48, v152, s6, v3
	s_movk_i32 s6, 0x210
	v_mov_b32_e32 v4, s7
	v_readlane_b32 s69, v254, 8
	v_mov_b32_e32 v9, 0
	v_lshl_add_u32 v56, v40, 2, 0
	v_mul_u32_u24_e32 v1, 0x110, v41
	v_lshlrev_b32_e32 v2, 8, v41
	v_or_b32_e32 v43, 64, v41
	v_add_u32_e32 v46, 0x8910, v3
	v_mul_u32_u24_e32 v3, 0x210, v252
	v_mad_u32_u24 v50, v252, s6, v4
	s_or_b64 s[4:5], s[18:19], s[4:5]
	v_readlane_b32 s84, v254, 27
	v_readlane_b32 s86, v254, 29
	v_readlane_b32 s88, v254, 31
	v_readlane_b32 s90, v254, 35
	s_mov_b32 s21, 0
	v_mul_u32_u24_e32 v57, 0x110, v42
	v_lshlrev_b32_e32 v58, 8, v42
	v_lshlrev_b32_e32 v59, 8, v43
	v_mul_u32_u24_e32 v60, 0x110, v44
	v_lshlrev_b32_e32 v61, 8, v44
	v_cmp_gt_u32_e64 s[0:1], 64, v253
	v_lshl_add_u64 v[20:21], s[68:69], 0, v[8:9]
	v_add_u32_e32 v45, 0, v0
	v_cmp_eq_u32_e64 s[8:9], 1, v252
	v_lshl_add_u64 v[22:23], s[58:59], 0, v[8:9]
	v_mul_i32_i24_e32 v49, 0xfffffef4, v152
	v_add_u32_e32 v51, v50, v8
	v_cmp_eq_u32_e64 s[10:11], 0, v152
	v_and_b32_e32 v62, 0xfc, v0
	s_and_b64 vcc, exec, s[4:5]
	v_lshl_add_u32 v52, v252, 8, 0
	v_add_u32_e32 v53, 0, v3
	v_lshlrev_b32_e32 v24, 1, v152
	v_add_u32_e32 v54, v56, v1
	v_add_u32_e32 v55, v56, v2
	v_readlane_b32 s85, v254, 28
	v_readlane_b32 s87, v254, 30
	v_readlane_b32 s89, v254, 32
	v_readlane_b32 s91, v254, 36
	v_readlane_b32 s93, v254, 38
	v_readlane_b32 s70, v254, 9
	v_readlane_b32 s71, v254, 10
	v_readlane_b32 s72, v254, 11
	v_readlane_b32 s73, v254, 12
	v_readlane_b32 s74, v254, 13
	v_readlane_b32 s75, v254, 14
	v_readlane_b32 s76, v254, 15
	v_readlane_b32 s77, v254, 16
	v_readlane_b32 s78, v254, 17
	v_readlane_b32 s79, v254, 18
	v_readlane_b32 s80, v254, 19
	v_readlane_b32 s81, v254, 20
	s_cbranch_vccnz .LBB0_325
	v_mbcnt_lo_u32_b32 v0, -1, 0
	v_mbcnt_hi_u32_b32 v0, -1, v0
	v_and_b32_e32 v1, 64, v0
	v_add_u32_e32 v1, 64, v1
	v_xor_b32_e32 v2, 1, v0
	v_cmp_lt_i32_e32 vcc, v2, v1
	s_movk_i32 s22, 0xfe00
	s_mov_b32 s23, -1
	v_cndmask_b32_e32 v2, v0, v2, vcc
	v_lshlrev_b32_e32 v14, 2, v2
	v_xor_b32_e32 v2, 2, v0
	v_cmp_lt_i32_e32 vcc, v2, v1
	v_mov_b32_e32 v27, 0x358637bd
	s_mov_b32 s12, 0x800000
	v_cndmask_b32_e32 v2, v0, v2, vcc
	v_lshlrev_b32_e32 v15, 2, v2
	v_xor_b32_e32 v2, 4, v0
	v_cmp_lt_i32_e32 vcc, v2, v1
	s_mov_b32 s13, s92
	s_nop 0
	v_cndmask_b32_e32 v2, v0, v2, vcc
	v_lshlrev_b32_e32 v16, 2, v2
	v_xor_b32_e32 v2, 8, v0
	v_cmp_lt_i32_e32 vcc, v2, v1
	s_nop 1
	v_cndmask_b32_e32 v2, v0, v2, vcc
	v_lshlrev_b32_e32 v17, 2, v2
	v_xor_b32_e32 v2, 16, v0
	v_cmp_lt_i32_e32 vcc, v2, v1
	s_nop 1
	v_cndmask_b32_e32 v2, v0, v2, vcc
	v_lshlrev_b32_e32 v18, 2, v2
	v_xor_b32_e32 v2, 32, v0
	v_cmp_lt_i32_e32 vcc, v2, v1
	s_nop 1
	v_cndmask_b32_e32 v0, v0, v2, vcc
	v_lshlrev_b32_e32 v19, 2, v0
	v_add_u32_e32 v0, 0, v62
	v_add_u32_e32 v26, 0x8910, v0
